# ph0 modulation GEMV: the 8 weight-row loads of a loop trip issued together with one wait instead of load/vmcnt(0) eight times
# speedup vs baseline: 1.0165x; 1.0165x over previous
; __device__ __forceinline__ void ph_mods(const TI ti, CArgs& a, unsigned char* ldsg) {
;     ...
; #pragma unroll 8
;         for (int k = w * 128; k < w * 128 + 128; ++k) {
;             const float wv = W[(size_t)k * 6144];
; #pragma unroll
;             for (int r = 0; r < 9; ++r) acc[r] += sc[r * 1024 + k] * wv;
;         }
.LBB0_923:
	v_lshl_add_u64 v[20:21], v[10:11], 0, s[46:47]
	s_mov_b64 s[98:99], 0x6000
	global_load_dword v70, v[20:21], off
	v_lshl_add_u64 v[86:87], v[20:21], 0, s[98:99]
	global_load_dword v72, v[86:87], off
	v_lshl_add_u64 v[88:89], v[86:87], 0, s[98:99]
	global_load_dword v74, v[88:89], off
	v_lshl_add_u64 v[86:87], v[88:89], 0, s[98:99]
	global_load_dword v76, v[86:87], off
	v_lshl_add_u64 v[88:89], v[86:87], 0, s[98:99]
	global_load_dword v78, v[88:89], off
	v_lshl_add_u64 v[86:87], v[88:89], 0, s[98:99]
	global_load_dword v80, v[86:87], off
	v_lshl_add_u64 v[88:89], v[86:87], 0, s[98:99]
	global_load_dword v82, v[88:89], off
	v_lshl_add_u64 v[86:87], v[88:89], 0, s[98:99]
	global_load_dword v84, v[86:87], off
	s_waitcnt vmcnt(0)
	ds_read_b128 v[28:31], v25
	ds_read_b128 v[2:5], v25 offset:16
	ds_read_b128 v[32:35], v25 offset:4096
	v_add_co_u32_e64 v64, s[40:41], s65, v20
	s_waitcnt lgkmcnt(2)
	v_mov_b32_e32 v36, v28
	v_addc_co_u32_e64 v65, s[40:41], 0, v21, s[40:41]
	s_waitcnt lgkmcnt(0)
	v_mov_b32_e32 v37, v32
	v_add_co_u32_e64 v28, s[40:41], s71, v20
	v_mov_b32_e32 v32, v29
	s_nop 0
	v_addc_co_u32_e64 v29, s[40:41], 0, v21, s[40:41]
	s_mov_b32 s4, 0x12000
	s_add_u32 s46, s46, 0x30000
	s_addc_u32 s47, s47, 0
	s_cmp_eq_u32 s46, 0x300000
	v_pk_fma_f32 v[16:17], v[70:71], v[36:37], v[16:17] op_sel_hi:[0,1,1]
	ds_read_b128 v[36:39], v25 offset:8192
	ds_read_b128 v[40:43], v25 offset:12288
	s_waitcnt lgkmcnt(1)
	v_mov_b32_e32 v44, v36
	s_waitcnt lgkmcnt(0)
	v_mov_b32_e32 v45, v40
	v_pk_fma_f32 v[18:19], v[70:71], v[44:45], v[18:19] op_sel_hi:[0,1,1]
	ds_read_b128 v[44:47], v25 offset:16384
	ds_read_b128 v[48:51], v25 offset:20480
	v_mov_b32_e32 v40, v37
	s_waitcnt lgkmcnt(1)
	v_mov_b32_e32 v52, v44
	s_waitcnt lgkmcnt(0)
	v_mov_b32_e32 v53, v48
	v_pk_fma_f32 v[14:15], v[70:71], v[52:53], v[14:15] op_sel_hi:[0,1,1]
	ds_read_b128 v[52:55], v25 offset:24576
	ds_read_b128 v[56:59], v25 offset:28672
	v_mov_b32_e32 v48, v45
	s_waitcnt lgkmcnt(1)
	v_mov_b32_e32 v60, v52
	s_waitcnt lgkmcnt(0)
	v_mov_b32_e32 v61, v56
	v_pk_fma_f32 v[12:13], v[70:71], v[60:61], v[12:13] op_sel_hi:[0,1,1]
	ds_read_b128 v[60:63], v25 offset:32768
	v_mov_b32_e32 v56, v53
	s_waitcnt lgkmcnt(0)
	v_fmac_f32_e32 v26, v70, v60
	v_pk_fma_f32 v[16:17], v[72:73], v[32:33], v[16:17] op_sel_hi:[0,1,1]
	v_pk_fma_f32 v[18:19], v[72:73], v[40:41], v[18:19] op_sel_hi:[0,1,1]
	v_pk_fma_f32 v[14:15], v[72:73], v[48:49], v[14:15] op_sel_hi:[0,1,1]
	v_pk_fma_f32 v[12:13], v[72:73], v[56:57], v[12:13] op_sel_hi:[0,1,1]
	v_fmac_f32_e32 v26, v72, v61
	v_mov_b32_e32 v28, v30
	v_mov_b32_e32 v29, v34
	v_mov_b32_e32 v34, v31
	v_mov_b32_e32 v32, v2
	v_pk_fma_f32 v[16:17], v[74:75], v[28:29], v[16:17] op_sel_hi:[0,1,1]
	v_mov_b32_e32 v28, v38
	v_mov_b32_e32 v29, v42
	v_pk_fma_f32 v[28:29], v[74:75], v[28:29], v[18:19] op_sel_hi:[0,1,1]
	v_mov_b32_e32 v18, v46
	v_mov_b32_e32 v19, v50
	v_pk_fma_f32 v[14:15], v[74:75], v[18:19], v[14:15] op_sel_hi:[0,1,1]
	v_mov_b32_e32 v18, v54
	v_mov_b32_e32 v19, v58
	v_pk_fma_f32 v[12:13], v[74:75], v[18:19], v[12:13] op_sel_hi:[0,1,1]
	v_add_co_u32_e64 v18, s[40:41], s4, v20
	v_fmac_f32_e32 v26, v74, v62
	s_nop 0
	v_addc_co_u32_e64 v19, s[40:41], 0, v21, s[40:41]
	v_mov_b32_e32 v42, v39
	v_mov_b32_e32 v50, v47
	v_mov_b32_e32 v58, v55
	s_mov_b32 s4, 0x1e000
	v_pk_fma_f32 v[18:19], v[76:77], v[34:35], v[16:17] op_sel_hi:[0,1,1]
	v_pk_fma_f32 v[16:17], v[76:77], v[42:43], v[28:29] op_sel_hi:[0,1,1]
	v_add_co_u32_e64 v28, s[40:41], s69, v20
	v_pk_fma_f32 v[14:15], v[76:77], v[50:51], v[14:15] op_sel_hi:[0,1,1]
	s_nop 0
	v_addc_co_u32_e64 v29, s[40:41], 0, v21, s[40:41]
	v_pk_fma_f32 v[12:13], v[76:77], v[58:59], v[12:13] op_sel_hi:[0,1,1]
	v_fmac_f32_e32 v26, v76, v63
	ds_read_b128 v[28:31], v25 offset:4112
	v_add_co_u32_e64 v60, s[40:41], s4, v20
	s_mov_b32 s4, 0x24000
	s_nop 0
	v_addc_co_u32_e64 v61, s[40:41], 0, v21, s[40:41]
	s_waitcnt lgkmcnt(0)
	v_mov_b32_e32 v33, v28
	v_mov_b32_e32 v28, v3
	v_pk_fma_f32 v[18:19], v[78:79], v[32:33], v[18:19] op_sel_hi:[0,1,1]
	ds_read_b128 v[32:35], v25 offset:8208
	ds_read_b128 v[36:39], v25 offset:12304
	s_waitcnt lgkmcnt(1)
	v_mov_b32_e32 v40, v32
	s_waitcnt lgkmcnt(0)
	v_mov_b32_e32 v41, v36
	v_pk_fma_f32 v[16:17], v[78:79], v[40:41], v[16:17] op_sel_hi:[0,1,1]
	ds_read_b128 v[40:43], v25 offset:16400
	ds_read_b128 v[44:47], v25 offset:20496
	v_mov_b32_e32 v36, v33
	s_waitcnt lgkmcnt(1)
	v_mov_b32_e32 v48, v40
	s_waitcnt lgkmcnt(0)
	v_mov_b32_e32 v49, v44
	v_pk_fma_f32 v[14:15], v[78:79], v[48:49], v[14:15] op_sel_hi:[0,1,1]
	ds_read_b128 v[48:51], v25 offset:24592
	ds_read_b128 v[52:55], v25 offset:28688
	v_mov_b32_e32 v44, v41
	s_waitcnt lgkmcnt(1)
	v_mov_b32_e32 v56, v48
	s_waitcnt lgkmcnt(0)
	v_mov_b32_e32 v57, v52
	v_pk_fma_f32 v[12:13], v[78:79], v[56:57], v[12:13] op_sel_hi:[0,1,1]
	ds_read_b128 v[56:59], v25 offset:32784
	v_mov_b32_e32 v52, v49
	v_add_u32_e32 v25, 32, v25
	s_waitcnt lgkmcnt(0)
	v_fmac_f32_e32 v26, v78, v56
	v_pk_fma_f32 v[2:3], v[80:81], v[28:29], v[18:19] op_sel_hi:[0,1,1]
	v_add_co_u32_e64 v18, s[40:41], s4, v20
	v_pk_fma_f32 v[16:17], v[80:81], v[36:37], v[16:17] op_sel_hi:[0,1,1]
	s_nop 0
	v_addc_co_u32_e64 v19, s[40:41], 0, v21, s[40:41]
	v_pk_fma_f32 v[14:15], v[80:81], v[44:45], v[14:15] op_sel_hi:[0,1,1]
	v_pk_fma_f32 v[12:13], v[80:81], v[52:53], v[12:13] op_sel_hi:[0,1,1]
	v_fmac_f32_e32 v26, v80, v57
	v_mov_b32_e32 v18, v4
	v_mov_b32_e32 v19, v30
	s_mov_b32 s4, 0x2a000
	v_mov_b32_e32 v30, v5
	v_pk_fma_f32 v[2:3], v[82:83], v[18:19], v[2:3] op_sel_hi:[0,1,1]
	v_mov_b32_e32 v18, v34
	v_mov_b32_e32 v19, v38
	v_pk_fma_f32 v[18:19], v[82:83], v[18:19], v[16:17] op_sel_hi:[0,1,1]
	v_mov_b32_e32 v16, v42
	v_mov_b32_e32 v17, v46
	v_pk_fma_f32 v[14:15], v[82:83], v[16:17], v[14:15] op_sel_hi:[0,1,1]
	v_mov_b32_e32 v16, v50
	v_mov_b32_e32 v17, v54
	v_pk_fma_f32 v[12:13], v[82:83], v[16:17], v[12:13] op_sel_hi:[0,1,1]
	v_add_co_u32_e64 v16, s[40:41], s4, v20
	v_fmac_f32_e32 v26, v82, v58
	s_nop 0
	v_addc_co_u32_e64 v17, s[40:41], 0, v21, s[40:41]
	v_mov_b32_e32 v38, v35
	v_mov_b32_e32 v46, v43
	v_mov_b32_e32 v54, v51
	v_pk_fma_f32 v[16:17], v[84:85], v[30:31], v[2:3] op_sel_hi:[0,1,1]
	v_pk_fma_f32 v[18:19], v[84:85], v[38:39], v[18:19] op_sel_hi:[0,1,1]
	v_pk_fma_f32 v[14:15], v[84:85], v[46:47], v[14:15] op_sel_hi:[0,1,1]
	v_pk_fma_f32 v[12:13], v[84:85], v[54:55], v[12:13] op_sel_hi:[0,1,1]
	v_fmac_f32_e32 v26, v84, v59
	s_cbranch_scc0 .LBB0_923
; __device__ __forceinline__ void ph_mods(const TI ti, CArgs& a, unsigned char* ldsg) {
;     ...
; #pragma unroll
;         for (int r = 0; r < 9; ++r) part[(w * 9 + r) * 64 + lane] = acc[r];
;         __syncthreads();
;         for (int idx = tid; idx < 576; idx += 512) {
;             const int r = idx >> 6, ln = idx & 63; float s = a.in[5][l * 6144 + n0 + ln];
;             for (int ww = 0; ww < 8; ++ww) s += part[(ww * 9 + r) * 64 + ln];
;             MOD[((size_t)l * 9 + r) * 6144 + n0 + ln] = s;
	ds_write2st64_b32 v24, v16, v17 offset0:144 offset1:145
	ds_write2st64_b32 v24, v18, v19 offset0:146 offset1:147
	ds_write2st64_b32 v24, v14, v15 offset0:148 offset1:149
	ds_write2st64_b32 v24, v12, v13 offset0:150 offset1:151
	ds_write_b32 v24, v26 offset:38912
	s_waitcnt lgkmcnt(0)
	s_barrier
	s_and_saveexec_b64 s[4:5], vcc
	s_cbranch_execz .LBB0_921
	s_mul_i32 s6, s3, 0x1800
	s_add_i32 s10, s6, s44
	v_or_b32_e32 v2, s10, v180
	v_ashrrev_i32_e32 v3, 31, v2
	s_mul_hi_i32 s7, s3, 9
	s_mul_i32 s6, s3, 9
	v_lshl_add_u64 v[2:3], v[2:3], 2, s[42:43]
	v_lshl_add_u64 v[4:5], s[44:45], 2, v[6:7]
	s_mov_b64 s[44:45], 0
	v_mov_b32_e32 v0, v178
